# tile-loop head: removed hipcc's vmcnt(0) inside the accumulator zeroing (drained epilogue stores every tile) in 5 GEMM instances
# baseline (speedup 1.0000x reference)
.LBB0_310:
	s_ashr_i32 s55, s54, 31
	s_lshl_b64 s[58:59], s[54:55], 19
	s_add_u32 s58, s29, s58
	s_addc_u32 s59, s30, s59
	s_and_b64 s[60:61], s[38:39], exec
	s_cselect_b32 s33, s59, s35
	s_cselect_b32 s36, s58, s34
	s_ashr_i32 s53, s52, 31
	s_lshl_b64 s[60:61], s[52:53], 19
	s_add_u32 s60, s45, s60
	s_addc_u32 s61, s66, s61
	s_and_b64 s[62:63], s[38:39], exec
	s_cselect_b32 s53, s61, s65
	s_cselect_b32 s55, s60, s64
	s_add_u32 s62, s34, 0x40080
	s_addc_u32 s63, s35, 0
	s_add_u32 s75, s64, 0x100
	v_mov_b32_e32 v0, 0
	s_addc_u32 s79, s65, 0
	s_mov_b32 s82, -2
	v_mov_b32_e32 v1, v0
	v_mov_b32_e32 v2, v0
	v_mov_b32_e32 v3, v0
	v_mov_b32_e32 v4, v0
	v_mov_b32_e32 v5, v0
	v_mov_b32_e32 v6, v0
	v_mov_b32_e32 v7, v0
	v_mov_b32_e32 v16, v0
	v_mov_b32_e32 v17, v0
	v_mov_b32_e32 v18, v0
	v_mov_b32_e32 v19, v0
	v_mov_b32_e32 v20, v0
	v_mov_b32_e32 v21, v0
	v_mov_b32_e32 v22, v0
	v_mov_b32_e32 v23, v0
	v_mov_b32_e32 v32, v0
	v_mov_b32_e32 v33, v0
	v_mov_b32_e32 v34, v0
	v_mov_b32_e32 v35, v0
	v_mov_b32_e32 v36, v0
	v_mov_b32_e32 v37, v0
	v_mov_b32_e32 v38, v0
	v_mov_b32_e32 v39, v0
	v_mov_b32_e32 v48, v0
	v_mov_b32_e32 v49, v0
	v_mov_b32_e32 v50, v0
	v_mov_b32_e32 v51, v0
	v_mov_b32_e32 v52, v0
	v_mov_b32_e32 v53, v0
	v_mov_b32_e32 v54, v0
	v_mov_b32_e32 v55, v0
	v_mov_b32_e32 v8, v0
	v_mov_b32_e32 v9, v0
	v_mov_b32_e32 v10, v0
	v_mov_b32_e32 v11, v0
	v_mov_b32_e32 v12, v0
	v_mov_b32_e32 v13, v0
	v_mov_b32_e32 v14, v0
	v_mov_b32_e32 v15, v0
	v_mov_b32_e32 v24, v0
	v_mov_b32_e32 v25, v0
	v_mov_b32_e32 v26, v0
	v_mov_b32_e32 v27, v0
	v_mov_b32_e32 v28, v0
	v_mov_b32_e32 v29, v0
	v_mov_b32_e32 v30, v0
	v_mov_b32_e32 v31, v0
	v_mov_b32_e32 v40, v0
	v_mov_b32_e32 v41, v0
	v_mov_b32_e32 v42, v0
	v_mov_b32_e32 v43, v0
	v_mov_b32_e32 v44, v0
	v_mov_b32_e32 v45, v0
	v_mov_b32_e32 v46, v0
	v_mov_b32_e32 v47, v0
	v_mov_b32_e32 v56, v0
	v_mov_b32_e32 v57, v0
	v_mov_b32_e32 v58, v0
	v_mov_b32_e32 v59, v0
	v_mov_b32_e32 v60, v0
	v_mov_b32_e32 v61, v0
	v_mov_b32_e32 v62, v0
	v_mov_b32_e32 v63, v0
	v_mov_b32_e32 v64, v0
	v_mov_b32_e32 v65, v0
	v_mov_b32_e32 v66, v0
	v_mov_b32_e32 v67, v0
	v_mov_b32_e32 v68, v0
	v_mov_b32_e32 v69, v0
	v_mov_b32_e32 v70, v0
	v_mov_b32_e32 v71, v0
	v_mov_b32_e32 v80, v0
	v_mov_b32_e32 v81, v0
	v_mov_b32_e32 v82, v0
	v_mov_b32_e32 v83, v0
	v_mov_b32_e32 v84, v0
	v_mov_b32_e32 v85, v0
	v_mov_b32_e32 v86, v0
	v_mov_b32_e32 v87, v0
	v_mov_b32_e32 v96, v0
	v_mov_b32_e32 v97, v0
	v_mov_b32_e32 v98, v0
	v_mov_b32_e32 v99, v0
	v_mov_b32_e32 v100, v0
	v_mov_b32_e32 v101, v0
	v_mov_b32_e32 v102, v0
	v_mov_b32_e32 v103, v0
	v_mov_b32_e32 v112, v0
	v_mov_b32_e32 v113, v0
	v_mov_b32_e32 v114, v0
	v_mov_b32_e32 v115, v0
	v_mov_b32_e32 v116, v0
	v_mov_b32_e32 v117, v0
	v_mov_b32_e32 v118, v0
	v_mov_b32_e32 v119, v0
	v_mov_b32_e32 v72, v0
	v_mov_b32_e32 v73, v0
	v_mov_b32_e32 v74, v0
	v_mov_b32_e32 v75, v0
	v_mov_b32_e32 v76, v0
	v_mov_b32_e32 v77, v0
	v_mov_b32_e32 v78, v0
	v_mov_b32_e32 v79, v0
	v_mov_b32_e32 v88, v0
	v_mov_b32_e32 v89, v0
	v_mov_b32_e32 v90, v0
	v_mov_b32_e32 v91, v0
	v_mov_b32_e32 v92, v0
	v_mov_b32_e32 v93, v0
	v_mov_b32_e32 v94, v0
	v_mov_b32_e32 v95, v0
	v_mov_b32_e32 v104, v0
	v_mov_b32_e32 v105, v0
	v_mov_b32_e32 v106, v0
	v_mov_b32_e32 v107, v0
	v_mov_b32_e32 v108, v0
	v_mov_b32_e32 v109, v0
	v_mov_b32_e32 v110, v0
	v_mov_b32_e32 v111, v0
	v_mov_b32_e32 v120, v0
	v_mov_b32_e32 v121, v0
	v_mov_b32_e32 v122, v0
	v_mov_b32_e32 v123, v0
	v_mov_b32_e32 v124, v0
	v_mov_b32_e32 v125, v0
	v_mov_b32_e32 v126, v0
	v_mov_b32_e32 v127, v0

.LBB0_604:
	s_ashr_i32 s71, s70, 31
	s_lshl_b64 s[34:35], s[70:71], 19
	s_cmp_eq_u32 s30, 0
	s_cselect_b32 s4, s29, s55
	s_cselect_b32 s3, s47, s46
	s_cselect_b32 s5, s53, s29
	s_cselect_b32 s71, s54, s47
	s_add_u32 s72, s4, s34
	s_addc_u32 s73, s3, s35
	s_and_b64 s[34:35], s[40:41], exec
	s_cselect_b32 s3, s73, s1
	s_cselect_b32 s36, s72, s0
	s_ashr_i32 s39, s38, 31
	s_lshl_b64 s[34:35], s[38:39], 19
	s_add_u32 s74, s5, s34
	s_addc_u32 s75, s71, s35
	s_and_b64 s[34:35], s[40:41], exec
	s_cselect_b32 s39, s75, s43
	s_cselect_b32 s71, s74, s42
	s_add_u32 s0, s0, 0x40080
	s_addc_u32 s1, s1, 0
	s_add_u32 s79, s42, 0x100
	v_mov_b32_e32 v0, 0
	s_addc_u32 s84, s43, 0
	s_mov_b32 s88, -2
	v_mov_b32_e32 v1, v0
	v_mov_b32_e32 v2, v0
	v_mov_b32_e32 v3, v0
	v_mov_b32_e32 v4, v0
	v_mov_b32_e32 v5, v0
	v_mov_b32_e32 v6, v0
	v_mov_b32_e32 v7, v0
	v_mov_b32_e32 v8, v0
	v_mov_b32_e32 v9, v0
	v_mov_b32_e32 v10, v0
	v_mov_b32_e32 v11, v0
	v_mov_b32_e32 v16, v0
	v_mov_b32_e32 v17, v0
	v_mov_b32_e32 v18, v0
	v_mov_b32_e32 v19, v0
	v_mov_b32_e32 v24, v0
	v_mov_b32_e32 v25, v0
	v_mov_b32_e32 v26, v0
	v_mov_b32_e32 v27, v0
	v_mov_b32_e32 v32, v0
	v_mov_b32_e32 v33, v0
	v_mov_b32_e32 v34, v0
	v_mov_b32_e32 v35, v0
	v_mov_b32_e32 v40, v0
	v_mov_b32_e32 v41, v0
	v_mov_b32_e32 v42, v0
	v_mov_b32_e32 v43, v0
	v_mov_b32_e32 v48, v0
	v_mov_b32_e32 v49, v0
	v_mov_b32_e32 v50, v0
	v_mov_b32_e32 v51, v0
	v_mov_b32_e32 v12, v0
	v_mov_b32_e32 v13, v0
	v_mov_b32_e32 v14, v0
	v_mov_b32_e32 v15, v0
	v_mov_b32_e32 v20, v0
	v_mov_b32_e32 v21, v0
	v_mov_b32_e32 v22, v0
	v_mov_b32_e32 v23, v0
	v_mov_b32_e32 v28, v0
	v_mov_b32_e32 v29, v0
	v_mov_b32_e32 v30, v0
	v_mov_b32_e32 v31, v0
	v_mov_b32_e32 v36, v0
	v_mov_b32_e32 v37, v0
	v_mov_b32_e32 v38, v0
	v_mov_b32_e32 v39, v0
	v_mov_b32_e32 v44, v0
	v_mov_b32_e32 v45, v0
	v_mov_b32_e32 v46, v0
	v_mov_b32_e32 v47, v0
	v_mov_b32_e32 v52, v0
	v_mov_b32_e32 v53, v0
	v_mov_b32_e32 v54, v0
	v_mov_b32_e32 v55, v0
	v_mov_b32_e32 v56, v0
	v_mov_b32_e32 v57, v0
	v_mov_b32_e32 v58, v0
	v_mov_b32_e32 v59, v0
	v_mov_b32_e32 v60, v0
	v_mov_b32_e32 v61, v0
	v_mov_b32_e32 v62, v0
	v_mov_b32_e32 v63, v0
	v_mov_b32_e32 v64, v0
	v_mov_b32_e32 v65, v0
	v_mov_b32_e32 v66, v0
	v_mov_b32_e32 v67, v0
	v_mov_b32_e32 v68, v0
	v_mov_b32_e32 v69, v0
	v_mov_b32_e32 v70, v0
	v_mov_b32_e32 v71, v0
	v_mov_b32_e32 v72, v0
	v_mov_b32_e32 v73, v0
	v_mov_b32_e32 v74, v0
	v_mov_b32_e32 v75, v0
	v_mov_b32_e32 v80, v0
	v_mov_b32_e32 v81, v0
	v_mov_b32_e32 v82, v0
	v_mov_b32_e32 v83, v0
	v_mov_b32_e32 v88, v0
	v_mov_b32_e32 v89, v0
	v_mov_b32_e32 v90, v0
	v_mov_b32_e32 v91, v0
	v_mov_b32_e32 v96, v0
	v_mov_b32_e32 v97, v0
	v_mov_b32_e32 v98, v0
	v_mov_b32_e32 v99, v0
	v_mov_b32_e32 v104, v0
	v_mov_b32_e32 v105, v0
	v_mov_b32_e32 v106, v0
	v_mov_b32_e32 v107, v0
	v_mov_b32_e32 v116, v0
	v_mov_b32_e32 v117, v0
	v_mov_b32_e32 v118, v0
	v_mov_b32_e32 v119, v0
	v_mov_b32_e32 v76, v0
	v_mov_b32_e32 v77, v0
	v_mov_b32_e32 v78, v0
	v_mov_b32_e32 v79, v0
	v_mov_b32_e32 v84, v0
	v_mov_b32_e32 v85, v0
	v_mov_b32_e32 v86, v0
	v_mov_b32_e32 v87, v0
	v_mov_b32_e32 v92, v0
	v_mov_b32_e32 v93, v0
	v_mov_b32_e32 v94, v0
	v_mov_b32_e32 v95, v0
	v_mov_b32_e32 v100, v0
	v_mov_b32_e32 v101, v0
	v_mov_b32_e32 v102, v0
	v_mov_b32_e32 v103, v0
	v_mov_b32_e32 v108, v0
	v_mov_b32_e32 v109, v0
	v_mov_b32_e32 v110, v0
	v_mov_b32_e32 v111, v0
	v_mov_b32_e32 v112, v0
	v_mov_b32_e32 v113, v0
	v_mov_b32_e32 v114, v0
	v_mov_b32_e32 v115, v0
	v_mov_b32_e32 v120, v0
	v_mov_b32_e32 v121, v0
	v_mov_b32_e32 v122, v0
	v_mov_b32_e32 v123, v0
	v_mov_b32_e32 v124, v0
	v_mov_b32_e32 v125, v0
	v_mov_b32_e32 v126, v0
	v_mov_b32_e32 v127, v0

.LBB0_1092:
	s_ashr_i32 s51, s50, 31
	s_lshl_b64 s[4:5], s[50:51], 18
	s_add_u32 s52, s29, s4
	s_addc_u32 s53, s30, s5
	s_and_b64 s[4:5], s[38:39], exec
	s_cselect_b32 s33, s53, s59
	s_cselect_b32 s36, s52, s58
	s_ashr_i32 s49, s48, 31
	s_lshl_b64 s[4:5], s[48:49], 18
	s_add_u32 s54, s62, s4
	s_addc_u32 s55, s63, s5
	s_and_b64 s[4:5], s[38:39], exec
	s_cselect_b32 s49, s55, s61
	s_cselect_b32 s51, s54, s60
	s_add_u32 s58, s58, 0x20080
	s_addc_u32 s59, s59, 0
	s_add_u32 s71, s60, 0x100
	v_mov_b32_e32 v0, 0
	s_addc_u32 s72, s61, 0
	s_mov_b32 s73, -2
	v_mov_b32_e32 v1, v0
	v_mov_b32_e32 v2, v0
	v_mov_b32_e32 v3, v0
	v_mov_b32_e32 v4, v0
	v_mov_b32_e32 v5, v0
	v_mov_b32_e32 v6, v0
	v_mov_b32_e32 v7, v0
	v_mov_b32_e32 v16, v0
	v_mov_b32_e32 v17, v0
	v_mov_b32_e32 v18, v0
	v_mov_b32_e32 v19, v0
	v_mov_b32_e32 v20, v0
	v_mov_b32_e32 v21, v0
	v_mov_b32_e32 v22, v0
	v_mov_b32_e32 v23, v0
	v_mov_b32_e32 v32, v0
	v_mov_b32_e32 v33, v0
	v_mov_b32_e32 v34, v0
	v_mov_b32_e32 v35, v0
	v_mov_b32_e32 v36, v0
	v_mov_b32_e32 v37, v0
	v_mov_b32_e32 v38, v0
	v_mov_b32_e32 v39, v0
	v_mov_b32_e32 v48, v0
	v_mov_b32_e32 v49, v0
	v_mov_b32_e32 v50, v0
	v_mov_b32_e32 v51, v0
	v_mov_b32_e32 v52, v0
	v_mov_b32_e32 v53, v0
	v_mov_b32_e32 v54, v0
	v_mov_b32_e32 v55, v0
	v_mov_b32_e32 v8, v0
	v_mov_b32_e32 v9, v0
	v_mov_b32_e32 v10, v0
	v_mov_b32_e32 v11, v0
	v_mov_b32_e32 v12, v0
	v_mov_b32_e32 v13, v0
	v_mov_b32_e32 v14, v0
	v_mov_b32_e32 v15, v0
	v_mov_b32_e32 v24, v0
	v_mov_b32_e32 v25, v0
	v_mov_b32_e32 v26, v0
	v_mov_b32_e32 v27, v0
	v_mov_b32_e32 v28, v0
	v_mov_b32_e32 v29, v0
	v_mov_b32_e32 v30, v0
	v_mov_b32_e32 v31, v0
	v_mov_b32_e32 v40, v0
	v_mov_b32_e32 v41, v0
	v_mov_b32_e32 v42, v0
	v_mov_b32_e32 v43, v0
	v_mov_b32_e32 v44, v0
	v_mov_b32_e32 v45, v0
	v_mov_b32_e32 v46, v0
	v_mov_b32_e32 v47, v0
	v_mov_b32_e32 v56, v0
	v_mov_b32_e32 v57, v0
	v_mov_b32_e32 v58, v0
	v_mov_b32_e32 v59, v0
	v_mov_b32_e32 v60, v0
	v_mov_b32_e32 v61, v0
	v_mov_b32_e32 v62, v0
	v_mov_b32_e32 v63, v0
	v_mov_b32_e32 v64, v0
	v_mov_b32_e32 v65, v0
	v_mov_b32_e32 v66, v0
	v_mov_b32_e32 v67, v0
	v_mov_b32_e32 v68, v0
	v_mov_b32_e32 v69, v0
	v_mov_b32_e32 v70, v0
	v_mov_b32_e32 v71, v0
	v_mov_b32_e32 v80, v0
	v_mov_b32_e32 v81, v0
	v_mov_b32_e32 v82, v0
	v_mov_b32_e32 v83, v0
	v_mov_b32_e32 v84, v0
	v_mov_b32_e32 v85, v0
	v_mov_b32_e32 v86, v0
	v_mov_b32_e32 v87, v0
	v_mov_b32_e32 v96, v0
	v_mov_b32_e32 v97, v0
	v_mov_b32_e32 v98, v0
	v_mov_b32_e32 v99, v0
	v_mov_b32_e32 v100, v0
	v_mov_b32_e32 v101, v0
	v_mov_b32_e32 v102, v0
	v_mov_b32_e32 v103, v0
	v_mov_b32_e32 v112, v0
	v_mov_b32_e32 v113, v0
	v_mov_b32_e32 v114, v0
	v_mov_b32_e32 v115, v0
	v_mov_b32_e32 v116, v0
	v_mov_b32_e32 v117, v0
	v_mov_b32_e32 v118, v0
	v_mov_b32_e32 v119, v0
	v_mov_b32_e32 v72, v0
	v_mov_b32_e32 v73, v0
	v_mov_b32_e32 v74, v0
	v_mov_b32_e32 v75, v0
	v_mov_b32_e32 v76, v0
	v_mov_b32_e32 v77, v0
	v_mov_b32_e32 v78, v0
	v_mov_b32_e32 v79, v0
	v_mov_b32_e32 v88, v0
	v_mov_b32_e32 v89, v0
	v_mov_b32_e32 v90, v0
	v_mov_b32_e32 v91, v0
	v_mov_b32_e32 v92, v0
	v_mov_b32_e32 v93, v0
	v_mov_b32_e32 v94, v0
	v_mov_b32_e32 v95, v0
	v_mov_b32_e32 v104, v0
	v_mov_b32_e32 v105, v0
	v_mov_b32_e32 v106, v0
	v_mov_b32_e32 v107, v0
	v_mov_b32_e32 v108, v0
	v_mov_b32_e32 v109, v0
	v_mov_b32_e32 v110, v0
	v_mov_b32_e32 v111, v0
	v_mov_b32_e32 v120, v0
	v_mov_b32_e32 v121, v0
	v_mov_b32_e32 v122, v0
	v_mov_b32_e32 v123, v0
	v_mov_b32_e32 v124, v0
	v_mov_b32_e32 v125, v0
	v_mov_b32_e32 v126, v0
	v_mov_b32_e32 v127, v0

.LBB0_1116:
	s_ashr_i32 s49, s48, 31
	s_lshl_b64 s[4:5], s[48:49], 18
	s_add_u32 s50, s30, s4
	s_addc_u32 s51, s60, s5
	s_and_b64 s[4:5], s[38:39], exec
	s_cselect_b32 s33, s51, s55
	s_cselect_b32 s36, s50, s54
	s_ashr_i32 s47, s46, 31
	s_lshl_b64 s[4:5], s[46:47], 18
	s_add_u32 s52, s61, s4
	s_addc_u32 s53, s62, s5
	s_and_b64 s[4:5], s[38:39], exec
	s_cselect_b32 s47, s53, s59
	s_cselect_b32 s49, s52, s58
	s_add_u32 s54, s54, 0x20080
	s_addc_u32 s55, s55, 0
	s_add_u32 s71, s58, 0x100
	v_mov_b32_e32 v0, 0
	s_addc_u32 s72, s59, 0
	s_mov_b32 s73, -2
	v_mov_b32_e32 v1, v0
	v_mov_b32_e32 v2, v0
	v_mov_b32_e32 v3, v0
	v_mov_b32_e32 v4, v0
	v_mov_b32_e32 v5, v0
	v_mov_b32_e32 v6, v0
	v_mov_b32_e32 v7, v0
	v_mov_b32_e32 v16, v0
	v_mov_b32_e32 v17, v0
	v_mov_b32_e32 v18, v0
	v_mov_b32_e32 v19, v0
	v_mov_b32_e32 v20, v0
	v_mov_b32_e32 v21, v0
	v_mov_b32_e32 v22, v0
	v_mov_b32_e32 v23, v0
	v_mov_b32_e32 v32, v0
	v_mov_b32_e32 v33, v0
	v_mov_b32_e32 v34, v0
	v_mov_b32_e32 v35, v0
	v_mov_b32_e32 v36, v0
	v_mov_b32_e32 v37, v0
	v_mov_b32_e32 v38, v0
	v_mov_b32_e32 v39, v0
	v_mov_b32_e32 v48, v0
	v_mov_b32_e32 v49, v0
	v_mov_b32_e32 v50, v0
	v_mov_b32_e32 v51, v0
	v_mov_b32_e32 v52, v0
	v_mov_b32_e32 v53, v0
	v_mov_b32_e32 v54, v0
	v_mov_b32_e32 v55, v0
	v_mov_b32_e32 v8, v0
	v_mov_b32_e32 v9, v0
	v_mov_b32_e32 v10, v0
	v_mov_b32_e32 v11, v0
	v_mov_b32_e32 v12, v0
	v_mov_b32_e32 v13, v0
	v_mov_b32_e32 v14, v0
	v_mov_b32_e32 v15, v0
	v_mov_b32_e32 v24, v0
	v_mov_b32_e32 v25, v0
	v_mov_b32_e32 v26, v0
	v_mov_b32_e32 v27, v0
	v_mov_b32_e32 v28, v0
	v_mov_b32_e32 v29, v0
	v_mov_b32_e32 v30, v0
	v_mov_b32_e32 v31, v0
	v_mov_b32_e32 v40, v0
	v_mov_b32_e32 v41, v0
	v_mov_b32_e32 v42, v0
	v_mov_b32_e32 v43, v0
	v_mov_b32_e32 v44, v0
	v_mov_b32_e32 v45, v0
	v_mov_b32_e32 v46, v0
	v_mov_b32_e32 v47, v0
	v_mov_b32_e32 v56, v0
	v_mov_b32_e32 v57, v0
	v_mov_b32_e32 v58, v0
	v_mov_b32_e32 v59, v0
	v_mov_b32_e32 v60, v0
	v_mov_b32_e32 v61, v0
	v_mov_b32_e32 v62, v0
	v_mov_b32_e32 v63, v0
	v_mov_b32_e32 v64, v0
	v_mov_b32_e32 v65, v0
	v_mov_b32_e32 v66, v0
	v_mov_b32_e32 v67, v0
	v_mov_b32_e32 v68, v0
	v_mov_b32_e32 v69, v0
	v_mov_b32_e32 v70, v0
	v_mov_b32_e32 v71, v0
	v_mov_b32_e32 v80, v0
	v_mov_b32_e32 v81, v0
	v_mov_b32_e32 v82, v0
	v_mov_b32_e32 v83, v0
	v_mov_b32_e32 v84, v0
	v_mov_b32_e32 v85, v0
	v_mov_b32_e32 v86, v0
	v_mov_b32_e32 v87, v0
	v_mov_b32_e32 v96, v0
	v_mov_b32_e32 v97, v0
	v_mov_b32_e32 v98, v0
	v_mov_b32_e32 v99, v0
	v_mov_b32_e32 v100, v0
	v_mov_b32_e32 v101, v0
	v_mov_b32_e32 v102, v0
	v_mov_b32_e32 v103, v0
	v_mov_b32_e32 v112, v0
	v_mov_b32_e32 v113, v0
	v_mov_b32_e32 v114, v0
	v_mov_b32_e32 v115, v0
	v_mov_b32_e32 v116, v0
	v_mov_b32_e32 v117, v0
	v_mov_b32_e32 v118, v0
	v_mov_b32_e32 v119, v0
	v_mov_b32_e32 v72, v0
	v_mov_b32_e32 v73, v0
	v_mov_b32_e32 v74, v0
	v_mov_b32_e32 v75, v0
	v_mov_b32_e32 v76, v0
	v_mov_b32_e32 v77, v0
	v_mov_b32_e32 v78, v0
	v_mov_b32_e32 v79, v0
	v_mov_b32_e32 v88, v0
	v_mov_b32_e32 v89, v0
	v_mov_b32_e32 v90, v0
	v_mov_b32_e32 v91, v0
	v_mov_b32_e32 v92, v0
	v_mov_b32_e32 v93, v0
	v_mov_b32_e32 v94, v0
	v_mov_b32_e32 v95, v0
	v_mov_b32_e32 v104, v0
	v_mov_b32_e32 v105, v0
	v_mov_b32_e32 v106, v0
	v_mov_b32_e32 v107, v0
	v_mov_b32_e32 v108, v0
	v_mov_b32_e32 v109, v0
	v_mov_b32_e32 v110, v0
	v_mov_b32_e32 v111, v0
	v_mov_b32_e32 v120, v0
	v_mov_b32_e32 v121, v0
	v_mov_b32_e32 v122, v0
	v_mov_b32_e32 v123, v0
	v_mov_b32_e32 v124, v0
	v_mov_b32_e32 v125, v0
	v_mov_b32_e32 v126, v0
	v_mov_b32_e32 v127, v0

.LBB0_1304:
	s_ashr_i32 s51, s50, 31
	s_lshl_b64 s[2:3], s[50:51], 19
	s_add_u32 s52, s28, s2
	s_addc_u32 s53, s29, s3
	s_and_b64 s[2:3], s[38:39], exec
	s_cselect_b32 s36, s53, s35
	s_cselect_b32 s51, s52, s34
	s_ashr_i32 s49, s48, 31
	s_lshl_b64 s[2:3], s[48:49], 19
	s_add_u32 s54, s30, s2
	s_addc_u32 s55, s62, s3
	s_and_b64 s[2:3], s[38:39], exec
	s_cselect_b32 s49, s55, s61
	s_cselect_b32 s70, s54, s60
	s_add_u32 s2, s34, 0x40080
	s_addc_u32 s3, s35, 0
	s_add_u32 s71, s60, 0x100
	v_mov_b32_e32 v0, 0
	s_addc_u32 s72, s61, 0
	s_mov_b32 s73, -2
	v_mov_b32_e32 v1, v0
	v_mov_b32_e32 v2, v0
	v_mov_b32_e32 v3, v0
	v_mov_b32_e32 v4, v0
	v_mov_b32_e32 v5, v0
	v_mov_b32_e32 v6, v0
	v_mov_b32_e32 v7, v0
	v_mov_b32_e32 v16, v0
	v_mov_b32_e32 v17, v0
	v_mov_b32_e32 v18, v0
	v_mov_b32_e32 v19, v0
	v_mov_b32_e32 v20, v0
	v_mov_b32_e32 v21, v0
	v_mov_b32_e32 v22, v0
	v_mov_b32_e32 v23, v0
	v_mov_b32_e32 v32, v0
	v_mov_b32_e32 v33, v0
	v_mov_b32_e32 v34, v0
	v_mov_b32_e32 v35, v0
	v_mov_b32_e32 v36, v0
	v_mov_b32_e32 v37, v0
	v_mov_b32_e32 v38, v0
	v_mov_b32_e32 v39, v0
	v_mov_b32_e32 v48, v0
	v_mov_b32_e32 v49, v0
	v_mov_b32_e32 v50, v0
	v_mov_b32_e32 v51, v0
	v_mov_b32_e32 v52, v0
	v_mov_b32_e32 v53, v0
	v_mov_b32_e32 v54, v0
	v_mov_b32_e32 v55, v0
	v_mov_b32_e32 v8, v0
	v_mov_b32_e32 v9, v0
	v_mov_b32_e32 v10, v0
	v_mov_b32_e32 v11, v0
	v_mov_b32_e32 v12, v0
	v_mov_b32_e32 v13, v0
	v_mov_b32_e32 v14, v0
	v_mov_b32_e32 v15, v0
	v_mov_b32_e32 v24, v0
	v_mov_b32_e32 v25, v0
	v_mov_b32_e32 v26, v0
	v_mov_b32_e32 v27, v0
	v_mov_b32_e32 v28, v0
	v_mov_b32_e32 v29, v0
	v_mov_b32_e32 v30, v0
	v_mov_b32_e32 v31, v0
	v_mov_b32_e32 v40, v0
	v_mov_b32_e32 v41, v0
	v_mov_b32_e32 v42, v0
	v_mov_b32_e32 v43, v0
	v_mov_b32_e32 v44, v0
	v_mov_b32_e32 v45, v0
	v_mov_b32_e32 v46, v0
	v_mov_b32_e32 v47, v0
	v_mov_b32_e32 v56, v0
	v_mov_b32_e32 v57, v0
	v_mov_b32_e32 v58, v0
	v_mov_b32_e32 v59, v0
	v_mov_b32_e32 v60, v0
	v_mov_b32_e32 v61, v0
	v_mov_b32_e32 v62, v0
	v_mov_b32_e32 v63, v0
	v_mov_b32_e32 v64, v0
	v_mov_b32_e32 v65, v0
	v_mov_b32_e32 v66, v0
	v_mov_b32_e32 v67, v0
	v_mov_b32_e32 v68, v0
	v_mov_b32_e32 v69, v0
	v_mov_b32_e32 v70, v0
	v_mov_b32_e32 v71, v0
	v_mov_b32_e32 v80, v0
	v_mov_b32_e32 v81, v0
	v_mov_b32_e32 v82, v0
	v_mov_b32_e32 v83, v0
	v_mov_b32_e32 v84, v0
	v_mov_b32_e32 v85, v0
	v_mov_b32_e32 v86, v0
	v_mov_b32_e32 v87, v0
	v_mov_b32_e32 v96, v0
	v_mov_b32_e32 v97, v0
	v_mov_b32_e32 v98, v0
	v_mov_b32_e32 v99, v0
	v_mov_b32_e32 v100, v0
	v_mov_b32_e32 v101, v0
	v_mov_b32_e32 v102, v0
	v_mov_b32_e32 v103, v0
	v_mov_b32_e32 v112, v0
	v_mov_b32_e32 v113, v0
	v_mov_b32_e32 v114, v0
	v_mov_b32_e32 v115, v0
	v_mov_b32_e32 v116, v0
	v_mov_b32_e32 v117, v0
	v_mov_b32_e32 v118, v0
	v_mov_b32_e32 v119, v0
	v_mov_b32_e32 v72, v0
	v_mov_b32_e32 v73, v0
	v_mov_b32_e32 v74, v0
	v_mov_b32_e32 v75, v0
	v_mov_b32_e32 v76, v0
	v_mov_b32_e32 v77, v0
	v_mov_b32_e32 v78, v0
	v_mov_b32_e32 v79, v0
	v_mov_b32_e32 v88, v0
	v_mov_b32_e32 v89, v0
	v_mov_b32_e32 v90, v0
	v_mov_b32_e32 v91, v0
	v_mov_b32_e32 v92, v0
	v_mov_b32_e32 v93, v0
	v_mov_b32_e32 v94, v0
	v_mov_b32_e32 v95, v0
	v_mov_b32_e32 v104, v0
	v_mov_b32_e32 v105, v0
	v_mov_b32_e32 v106, v0
	v_mov_b32_e32 v107, v0
	v_mov_b32_e32 v108, v0
	v_mov_b32_e32 v109, v0
	v_mov_b32_e32 v110, v0
	v_mov_b32_e32 v111, v0
	v_mov_b32_e32 v120, v0
	v_mov_b32_e32 v121, v0
	v_mov_b32_e32 v122, v0
	v_mov_b32_e32 v123, v0
	v_mov_b32_e32 v124, v0
	v_mov_b32_e32 v125, v0
	v_mov_b32_e32 v126, v0
	v_mov_b32_e32 v127, v0
